# v49 + residual-epilogue src loads nontemporal
# baseline (speedup 1.0000x reference)
;     DI void operator()(const f32x4 (&acc)[2][2][4][2], const Unit& u, int wr, int wc, int fr, int fq) const {
;         const bool isc = u.pm >= (TL / BM);
;         const int bi = isc ? 16 : (u.pm >> 4);
;         const int rloc = (isc ? (u.pm - TL / BM) : u.pm) * BM + wr * 64 + fr;
;         const float* src = isc ? srcC : srcL; float* dst = isc ? dstC : dstL;
;         const int col0 = u.pn * BM + wc * 32 + 8 * fq;
;         const float* gp = gate + (size_t)bi * MODW + col0;
;         f32x4 gv[2][2];
; #pragma unroll
;         for (int bj = 0; bj < 2; ++bj)
; #pragma unroll
;             for (int n = 0; n < 2; ++n) gv[bj][n] = *(const f32x4*)(gp + bj * HALF + 4 * n) * coef;
; #pragma unroll
;         for (int ai = 0; ai < 2; ++ai)
; #pragma unroll
;             for (int mp = 0; mp < 2; ++mp) {
;                 f32x4 sv[2][2][2];
; #pragma unroll
;                 for (int m = 0; m < 2; ++m)
; #pragma unroll
;                     for (int bj = 0; bj < 2; ++bj)
; #pragma unroll
;                         for (int n = 0; n < 2; ++n) sv[m][bj][n] = *(const f32x4*)(src + (size_t)(rloc + ai * HALF + (2 * mp + m) * 16) * DM + col0 + bj * HALF + 4 * n);
; #pragma unroll
;                 for (int m = 0; m < 2; ++m)
; #pragma unroll
;                     for (int bj = 0; bj < 2; ++bj)
; #pragma unroll
;                         for (int n = 0; n < 2; ++n) *(f32x4*)(dst + (size_t)(rloc + ai * HALF + (2 * mp + m) * 16) * DM + col0 + bj * HALF + 4 * n) = sv[m][bj][n] + gv[bj][n] * acc[ai][bj][2 * mp + m][n];
;             }
.LBB0_498:
	s_lshl_b32 s22, s22, 8
	s_add_i32 s33, s22, 0xffff0000
	s_and_b64 s[30:31], exec, s[88:89]
	s_cselect_b32 s22, s33, s22
	v_lshl_or_b32 v184, s26, 8, v170
	s_lshl_b64 s[30:31], s[90:91], 2
	s_add_u32 s30, s68, s30
	s_addc_u32 s31, s69, s31
	v_lshlrev_b32_e32 v184, 2, v184
	v_add_u32_e32 v160, s22, v165
	s_nop 0
	global_load_dwordx4 v[140:143], v184, s[30:31]
	global_load_dwordx4 v[144:147], v184, s[30:31] offset:16
	global_load_dwordx4 v[148:151], v184, s[30:31] offset:512
	global_load_dwordx4 v[152:155], v184, s[30:31] offset:528
	v_lshl_add_u32 v160, v160, 12, v184
	v_add_u32_e32 v161, 0x10000, v160
	v_add_u32_e32 v166, 0x20000, v160
	v_add_u32_e32 v167, 0x30000, v160
	v_add_u32_e32 v156, 0x80000, v160
	v_add_u32_e32 v157, 0x90000, v160
	v_add_u32_e32 v158, 0xa0000, v160
	v_add_u32_e32 v159, 0xb0000, v160
	global_load_dwordx4 v[196:199], v160, s[86:87] nt
	global_load_dwordx4 v[200:203], v160, s[86:87] offset:16 nt
	global_load_dwordx4 v[204:207], v160, s[86:87] offset:512 nt
	global_load_dwordx4 v[208:211], v160, s[86:87] offset:528 nt
	global_load_dwordx4 v[212:215], v161, s[86:87] nt
	global_load_dwordx4 v[216:219], v161, s[86:87] offset:16 nt
	global_load_dwordx4 v[220:223], v161, s[86:87] offset:512 nt
	global_load_dwordx4 v[224:227], v161, s[86:87] offset:528 nt
	global_load_dwordx4 v[228:231], v166, s[86:87] nt
	global_load_dwordx4 v[232:235], v166, s[86:87] offset:16 nt
	global_load_dwordx4 v[236:239], v166, s[86:87] offset:512 nt
	global_load_dwordx4 v[240:243], v166, s[86:87] offset:528 nt
	global_load_dwordx4 v[244:247], v167, s[86:87] nt
	global_load_dwordx4 v[248:251], v167, s[86:87] offset:16 nt
	global_load_dwordx4 v[172:175], v167, s[86:87] offset:512 nt
	global_load_dwordx4 v[176:179], v167, s[86:87] offset:528 nt
	s_waitcnt vmcnt(16)
	v_pk_mul_f32 v[140:141], s[70:71], v[140:141]
	v_pk_mul_f32 v[142:143], s[78:79], v[142:143]
	v_pk_mul_f32 v[144:145], s[70:71], v[144:145]
	v_pk_mul_f32 v[146:147], s[78:79], v[146:147]
	v_pk_mul_f32 v[148:149], s[70:71], v[148:149]
	v_pk_mul_f32 v[150:151], s[78:79], v[150:151]
	v_pk_mul_f32 v[152:153], s[70:71], v[152:153]
	v_pk_mul_f32 v[154:155], s[78:79], v[154:155]
	s_waitcnt vmcnt(0)
	v_pk_fma_f32 v[126:127], v[126:127], v[140:141], v[196:197]
	v_pk_fma_f32 v[128:129], v[128:129], v[142:143], v[198:199]
	v_pk_fma_f32 v[122:123], v[122:123], v[144:145], v[200:201]
	v_pk_fma_f32 v[124:125], v[124:125], v[146:147], v[202:203]
	v_pk_fma_f32 v[110:111], v[110:111], v[148:149], v[204:205]
	v_pk_fma_f32 v[112:113], v[112:113], v[150:151], v[206:207]
	v_pk_fma_f32 v[106:107], v[106:107], v[152:153], v[208:209]
	v_pk_fma_f32 v[108:109], v[108:109], v[154:155], v[210:211]
	v_pk_fma_f32 v[118:119], v[118:119], v[140:141], v[212:213]
	v_pk_fma_f32 v[120:121], v[120:121], v[142:143], v[214:215]
	v_pk_fma_f32 v[114:115], v[114:115], v[144:145], v[216:217]
	v_pk_fma_f32 v[116:117], v[116:117], v[146:147], v[218:219]
	v_pk_fma_f32 v[102:103], v[102:103], v[148:149], v[220:221]
	v_pk_fma_f32 v[104:105], v[104:105], v[150:151], v[222:223]
	v_pk_fma_f32 v[98:99], v[98:99], v[152:153], v[224:225]
	v_pk_fma_f32 v[100:101], v[100:101], v[154:155], v[226:227]
	v_pk_fma_f32 v[94:95], v[94:95], v[140:141], v[228:229]
	v_pk_fma_f32 v[96:97], v[96:97], v[142:143], v[230:231]
	v_pk_fma_f32 v[90:91], v[90:91], v[144:145], v[232:233]
	v_pk_fma_f32 v[92:93], v[92:93], v[146:147], v[234:235]
	v_pk_fma_f32 v[78:79], v[78:79], v[148:149], v[236:237]
	v_pk_fma_f32 v[80:81], v[80:81], v[150:151], v[238:239]
	v_pk_fma_f32 v[74:75], v[74:75], v[152:153], v[240:241]
	v_pk_fma_f32 v[76:77], v[76:77], v[154:155], v[242:243]
	v_pk_fma_f32 v[86:87], v[86:87], v[140:141], v[244:245]
	v_pk_fma_f32 v[88:89], v[88:89], v[142:143], v[246:247]
	v_pk_fma_f32 v[82:83], v[82:83], v[144:145], v[248:249]
	v_pk_fma_f32 v[84:85], v[84:85], v[146:147], v[250:251]
	v_pk_fma_f32 v[70:71], v[70:71], v[148:149], v[172:173]
	v_pk_fma_f32 v[72:73], v[72:73], v[150:151], v[174:175]
	v_pk_fma_f32 v[66:67], v[66:67], v[152:153], v[176:177]
	v_pk_fma_f32 v[68:69], v[68:69], v[154:155], v[178:179]
	global_load_dwordx4 v[196:199], v156, s[86:87] nt
	global_load_dwordx4 v[200:203], v156, s[86:87] offset:16 nt
	global_load_dwordx4 v[204:207], v156, s[86:87] offset:512 nt
	global_load_dwordx4 v[208:211], v156, s[86:87] offset:528 nt
	global_load_dwordx4 v[212:215], v157, s[86:87] nt
	global_load_dwordx4 v[216:219], v157, s[86:87] offset:16 nt
	global_load_dwordx4 v[220:223], v157, s[86:87] offset:512 nt
	global_load_dwordx4 v[224:227], v157, s[86:87] offset:528 nt
	global_load_dwordx4 v[228:231], v158, s[86:87] nt
	global_load_dwordx4 v[232:235], v158, s[86:87] offset:16 nt
	global_load_dwordx4 v[236:239], v158, s[86:87] offset:512 nt
	global_load_dwordx4 v[240:243], v158, s[86:87] offset:528 nt
	global_load_dwordx4 v[244:247], v159, s[86:87] nt
	global_load_dwordx4 v[248:251], v159, s[86:87] offset:16 nt
	global_load_dwordx4 v[172:175], v159, s[86:87] offset:512 nt
	global_load_dwordx4 v[176:179], v159, s[86:87] offset:528 nt
	global_store_dwordx4 v160, v[126:129], s[84:85]
	global_store_dwordx4 v160, v[122:125], s[84:85] offset:16
	global_store_dwordx4 v160, v[110:113], s[84:85] offset:512
	global_store_dwordx4 v160, v[106:109], s[84:85] offset:528
	global_store_dwordx4 v161, v[118:121], s[84:85]
	global_store_dwordx4 v161, v[114:117], s[84:85] offset:16
	global_store_dwordx4 v161, v[102:105], s[84:85] offset:512
	global_store_dwordx4 v161, v[98:101], s[84:85] offset:528
	global_store_dwordx4 v166, v[94:97], s[84:85]
	global_store_dwordx4 v166, v[90:93], s[84:85] offset:16
	global_store_dwordx4 v166, v[78:81], s[84:85] offset:512
	global_store_dwordx4 v166, v[74:77], s[84:85] offset:528
	global_store_dwordx4 v167, v[86:89], s[84:85]
	global_store_dwordx4 v167, v[82:85], s[84:85] offset:16
	global_store_dwordx4 v167, v[70:73], s[84:85] offset:512
	global_store_dwordx4 v167, v[66:69], s[84:85] offset:528
	s_waitcnt vmcnt(16)
; #define PG8_BAR __builtin_amdgcn_s_barrier()
; template <class Epi>
; DI void gemm_phase(LAS unsigned char* lds, int tid, const Gemm g, const Order& S, const Epi& E) {
;     ...
;         if (!has_next) break;
; #pragma unroll
;         for (int a = 0; a < 2; ++a)
; #pragma unroll
;             for (int b = 0; b < 2; ++b)
; #pragma unroll
;                 for (int m = 0; m < 4; ++m)
; #pragma unroll
;                     for (int n = 0; n < 2; ++n) acc[a][b][m][n] = (f32x4){0.f, 0.f, 0.f, 0.f};
;         cur = nxt; cA = nA; cB = nB; ++ui;
;         if (wr == 1) PG8_BAR;
;     DI void operator()(const f32x4 (&acc)[2][2][4][2], const Unit& u, int wr, int wc, int fr, int fq) const {
;     ...
;                 for (int m = 0; m < 2; ++m)
; #pragma unroll
;                     for (int bj = 0; bj < 2; ++bj)
; #pragma unroll
;                         for (int n = 0; n < 2; ++n) *(f32x4*)(dst + (size_t)(rloc + ai * HALF + (2 * mp + m) * 16) * DM + col0 + bj * HALF + 4 * n) = sv[m][bj][n] + gv[bj][n] * acc[ai][bj][2 * mp + m][n];
;             }
	v_pk_fma_f32 v[62:63], v[62:63], v[140:141], v[196:197]
	v_pk_fma_f32 v[64:65], v[64:65], v[142:143], v[198:199]
	v_pk_fma_f32 v[58:59], v[58:59], v[144:145], v[200:201]
	v_pk_fma_f32 v[60:61], v[60:61], v[146:147], v[202:203]
	v_pk_fma_f32 v[46:47], v[46:47], v[148:149], v[204:205]
	v_pk_fma_f32 v[48:49], v[48:49], v[150:151], v[206:207]
	v_pk_fma_f32 v[42:43], v[42:43], v[152:153], v[208:209]
	v_pk_fma_f32 v[44:45], v[44:45], v[154:155], v[210:211]
	v_pk_fma_f32 v[54:55], v[54:55], v[140:141], v[212:213]
	v_pk_fma_f32 v[56:57], v[56:57], v[142:143], v[214:215]
	v_pk_fma_f32 v[50:51], v[50:51], v[144:145], v[216:217]
	v_pk_fma_f32 v[52:53], v[52:53], v[146:147], v[218:219]
	v_pk_fma_f32 v[38:39], v[38:39], v[148:149], v[220:221]
	v_pk_fma_f32 v[40:41], v[40:41], v[150:151], v[222:223]
	v_pk_fma_f32 v[34:35], v[34:35], v[152:153], v[224:225]
	v_pk_fma_f32 v[36:37], v[36:37], v[154:155], v[226:227]
	v_pk_fma_f32 v[30:31], v[30:31], v[140:141], v[228:229]
	v_pk_fma_f32 v[32:33], v[32:33], v[142:143], v[230:231]
	v_pk_fma_f32 v[26:27], v[26:27], v[144:145], v[232:233]
	v_pk_fma_f32 v[28:29], v[28:29], v[146:147], v[234:235]
	v_pk_fma_f32 v[14:15], v[14:15], v[148:149], v[236:237]
	v_pk_fma_f32 v[16:17], v[16:17], v[150:151], v[238:239]
	v_pk_fma_f32 v[10:11], v[10:11], v[152:153], v[240:241]
	v_pk_fma_f32 v[12:13], v[12:13], v[154:155], v[242:243]
	v_pk_fma_f32 v[22:23], v[22:23], v[140:141], v[244:245]
	v_pk_fma_f32 v[24:25], v[24:25], v[142:143], v[246:247]
	v_pk_fma_f32 v[18:19], v[18:19], v[144:145], v[248:249]
	v_pk_fma_f32 v[20:21], v[20:21], v[146:147], v[250:251]
	v_pk_fma_f32 v[6:7], v[6:7], v[148:149], v[172:173]
	v_pk_fma_f32 v[8:9], v[8:9], v[150:151], v[174:175]
	v_pk_fma_f32 v[2:3], v[2:3], v[152:153], v[176:177]
	v_pk_fma_f32 v[4:5], v[4:5], v[154:155], v[178:179]
	global_store_dwordx4 v156, v[62:65], s[84:85]
	global_store_dwordx4 v156, v[58:61], s[84:85] offset:16
	global_store_dwordx4 v156, v[46:49], s[84:85] offset:512
	global_store_dwordx4 v156, v[42:45], s[84:85] offset:528
	global_store_dwordx4 v157, v[54:57], s[84:85]
	global_store_dwordx4 v157, v[50:53], s[84:85] offset:16
	global_store_dwordx4 v157, v[38:41], s[84:85] offset:512
	global_store_dwordx4 v157, v[34:37], s[84:85] offset:528
	global_store_dwordx4 v158, v[30:33], s[84:85]
	global_store_dwordx4 v158, v[26:29], s[84:85] offset:16
	global_store_dwordx4 v158, v[14:17], s[84:85] offset:512
	global_store_dwordx4 v158, v[10:13], s[84:85] offset:528
	global_store_dwordx4 v159, v[22:25], s[84:85]
	global_store_dwordx4 v159, v[18:21], s[84:85] offset:16
	global_store_dwordx4 v159, v[6:9], s[84:85] offset:512
	global_store_dwordx4 v159, v[2:5], s[84:85] offset:528
	s_mov_b64 s[84:85], -1
	s_and_b64 vcc, exec, s[4:5]
	s_cbranch_vccnz .LBB0_485
	s_andn2_b64 vcc, exec, s[76:77]
	s_cbranch_vccnz .LBB0_484
	s_barrier
	s_branch .LBB0_484
